# sweep-2 softmax exponent scaling: scalar v_fmamk pairs packed into v_pk_fma_f32 with broadcast addend pairs (same fused arithmetic)
# baseline (speedup 1.0000x reference)
; #define SBAR() __builtin_amdgcn_sched_barrier(0)
; __device__ __forceinline__ void stat_upd(const f32x16& p0, float& m, float& l, const float C, const float cb) {
;   float mx = p0[0];
; #pragma unroll
;   for (int r = 1; r < 16; ++r) mx = fmaxf(mx, p0[r]);
;   { auto rr = __builtin_amdgcn_permlane32_swap(__float_as_uint(mx), __float_as_uint(mx), false, false);
;     mx = fmaxf(__uint_as_float(rr[0]), __uint_as_float(rr[1])); }
;   mx += cb;
;   const float mn = fmaxf(m, mx), alpha = __builtin_amdgcn_exp2f((m - mn) * C), mnC = (cb - mn) * C; float s = 0.f;
; #pragma unroll
;   for (int r = 0; r < 16; ++r) s += __builtin_amdgcn_exp2f(fmaf(p0[r], C, mnC));
;   l = l * alpha + s; m = mn;
; }
; template <bool DIFF> ...
;     ...
;       stat_upd(a0, m1, l1, C, cb0);
;       if (DIFF) stat_upd(b0, m2, l2, C, cb0);
;       SBAR();
;       BIAS_APPLY(t, 1, a1, b1, cb1);
;       stat_upd(a1, m1, l1, C, cb1);
;       if (DIFF) stat_upd(b1, m2, l2, C, cb1);
.LBB0_308:
	s_or_b64 exec, exec, s[34:35]
	v_max_f32_e32 v0, v0, v0
	v_max_f32_e32 v69, v69, v69
	v_max_f32_e32 v0, v0, v69
	s_waitcnt lgkmcnt(0)
	v_add_f32_e32 v0, v1, v0
	v_max_f32_e32 v69, v87, v87
	v_max_f32_e32 v69, v69, v0
	v_sub_f32_e32 v0, v1, v69
	v_mul_f32_e32 v70, 0x3e38aa3b, v0
	v_fmamk_f32 v0, v50, 0x3e38aa3b, v70
	v_exp_f32_e32 v50, v0
	v_fmamk_f32 v0, v51, 0x3e38aa3b, v70
	v_exp_f32_e32 v51, v0
	s_lshl_b64 s[6:7], s[6:7], 1
	v_add_f32_e32 v50, 0, v50
	s_add_u32 s2, s44, s6
	v_add_f32_e32 v50, v51, v50
	v_fmamk_f32 v51, v52, 0x3e38aa3b, v70
	v_exp_f32_e32 v51, v51
	v_fmamk_f32 v52, v53, 0x3e38aa3b, v70
	v_exp_f32_e32 v52, v52
	v_fmamk_f32 v53, v54, 0x3e38aa3b, v70
	v_exp_f32_e32 v53, v53
	v_fmamk_f32 v54, v55, 0x3e38aa3b, v70
	v_exp_f32_e32 v54, v54
	v_add_f32_e32 v50, v51, v50
	v_fmamk_f32 v51, v56, 0x3e38aa3b, v70
	v_add_f32_e32 v50, v52, v50
	v_exp_f32_e32 v51, v51
	v_fmamk_f32 v52, v57, 0x3e38aa3b, v70
	v_add_f32_e32 v50, v53, v50
	v_exp_f32_e32 v52, v52
	v_fmamk_f32 v53, v58, 0x3e38aa3b, v70
	v_add_f32_e32 v50, v54, v50
	v_exp_f32_e32 v53, v53
	v_fmamk_f32 v54, v59, 0x3e38aa3b, v70
	v_exp_f32_e32 v54, v54
	v_add_f32_e32 v50, v51, v50
	v_fmamk_f32 v51, v60, 0x3e38aa3b, v70
	v_add_f32_e32 v50, v52, v50
	v_exp_f32_e32 v51, v51
	v_fmamk_f32 v52, v61, 0x3e38aa3b, v70
	v_add_f32_e32 v50, v53, v50
	v_exp_f32_e32 v52, v52
	v_fmamk_f32 v53, v62, 0x3e38aa3b, v70
	v_add_f32_e32 v50, v54, v50
	v_exp_f32_e32 v53, v53
	v_fmamk_f32 v54, v63, 0x3e38aa3b, v70
	v_exp_f32_e32 v54, v54
	v_add_f32_e32 v50, v51, v50
	v_add_f32_e32 v50, v52, v50
	v_add_f32_e32 v50, v53, v50
	v_add_f32_e32 v50, v54, v50
	v_max_f32_e32 v54, v66, v66
	v_max_f32_e32 v55, v67, v67
	v_max_f32_e32 v54, v54, v55
	v_add_f32_e32 v54, v1, v54
	v_max_f32_e32 v55, v81, v81
	v_max_f32_e32 v54, v55, v54
	v_sub_f32_e32 v1, v1, v54
	v_mul_f32_e32 v1, 0x3e38aa3b, v1
	v_fmamk_f32 v34, v34, 0x3e38aa3b, v1
	v_exp_f32_e32 v34, v34
	v_fmamk_f32 v35, v35, 0x3e38aa3b, v1
	v_exp_f32_e32 v35, v35
	v_fmamk_f32 v36, v36, 0x3e38aa3b, v1
	v_exp_f32_e32 v36, v36
	v_fmamk_f32 v37, v37, 0x3e38aa3b, v1
	v_add_f32_e32 v34, 0, v34
	v_exp_f32_e32 v37, v37
	v_fmamk_f32 v38, v38, 0x3e38aa3b, v1
	v_exp_f32_e32 v38, v38
	v_add_f32_e32 v34, v35, v34
	v_fmamk_f32 v35, v39, 0x3e38aa3b, v1
	v_add_f32_e32 v34, v36, v34
	v_exp_f32_e32 v35, v35
	v_fmamk_f32 v36, v40, 0x3e38aa3b, v1
	v_exp_f32_e32 v36, v36
	v_add_f32_e32 v34, v37, v34
	v_fmamk_f32 v37, v41, 0x3e38aa3b, v1
	v_add_f32_e32 v34, v38, v34
	v_exp_f32_e32 v37, v37
	v_fmamk_f32 v38, v42, 0x3e38aa3b, v1
	v_exp_f32_e32 v38, v38
	v_add_f32_e32 v34, v35, v34
	v_fmamk_f32 v35, v43, 0x3e38aa3b, v1
	v_add_f32_e32 v34, v36, v34
	v_exp_f32_e32 v35, v35
	v_fmamk_f32 v36, v44, 0x3e38aa3b, v1
	v_exp_f32_e32 v36, v36
	v_add_f32_e32 v34, v37, v34
	v_fmamk_f32 v37, v45, 0x3e38aa3b, v1
	v_add_f32_e32 v34, v38, v34
	v_exp_f32_e32 v37, v37
	v_fmamk_f32 v38, v46, 0x3e38aa3b, v1
	v_exp_f32_e32 v38, v38
	v_add_f32_e32 v34, v35, v34
	v_fmamk_f32 v35, v47, 0x3e38aa3b, v1
	v_add_f32_e32 v34, v36, v34
	v_exp_f32_e32 v35, v35
	v_fmamk_f32 v36, v48, 0x3e38aa3b, v1
	v_exp_f32_e32 v36, v36
	v_fmac_f32_e32 v1, 0x3e38aa3b, v49
	v_add_f32_e32 v34, v37, v34
	v_exp_f32_e32 v1, v1
	v_sub_f32_e32 v37, v81, v54
	v_add_f32_e32 v34, v38, v34
	v_mul_f32_e32 v37, 0x3e38aa3b, v37
	v_exp_f32_e32 v37, v37
	v_add_f32_e32 v34, v35, v34
	v_add_f32_e32 v34, v36, v34
	v_add_f32_e32 v1, v1, v34
	v_lshlrev_b32_e32 v34, 1, v80
	v_and_b32_e32 v38, 0xfffff0, v86
	v_lshlrev_b32_e32 v39, 1, v86
	v_and_b32_e32 v43, 0xfffff0, v80
	v_and_or_b32 v38, v39, 8, v38
	v_lshlrev_b32_e32 v40, 4, v75
	v_and_or_b32 v34, v34, 8, v43
	v_fmac_f32_e32 v1, v82, v37
	v_lshrrev_b32_e32 v35, 1, v80
	v_lshrrev_b32_e32 v36, 5, v72
	v_and_b32_e32 v37, 3, v80
	v_lshrrev_b32_e32 v38, 1, v38
	v_lshlrev_b32_e32 v39, 3, v75
	v_and_b32_e32 v40, 0xc0, v40
	v_lshrrev_b32_e32 v34, 1, v34
	v_and_b32_e32 v42, 0x100, v39
	v_or_b32_e32 v34, v34, v36
	v_and_or_b32 v35, v35, 4, v37
	v_or_b32_e32 v36, v38, v36
	v_and_or_b32 v37, v39, 24, v40
	v_max_f32_e32 v38, v19, v19
	v_max_f32_e32 v39, v18, v18
	v_max_f32_e32 v38, v39, v38
	v_max3_f32 v38, v38, v20, v21
	v_max3_f32 v38, v38, v22, v23
	v_max3_f32 v38, v38, v24, v25
	v_max3_f32 v38, v38, v26, v27
	v_max3_f32 v38, v38, v28, v29
	v_max3_f32 v38, v38, v30, v31
	v_max3_f32 v38, v38, v32, v33
	v_mov_b32_e32 v39, v38
	s_nop 1
	v_permlane32_swap_b32_e32 v38, v39
	v_max_f32_e32 v39, v39, v39
	v_max_f32_e32 v38, v38, v38
	v_max_f32_e32 v38, v38, v39
	v_add_f32_e32 v38, v68, v38
	v_max_f32_e32 v38, v69, v38
	v_sub_f32_e32 v39, v68, v38
	v_mul_f32_e32 v39, 0x3e38aa3b, v39
	v_fmamk_f32 v18, v18, 0x3e38aa3b, v39
	v_exp_f32_e32 v18, v18
	v_fmamk_f32 v19, v19, 0x3e38aa3b, v39
	v_exp_f32_e32 v19, v19
	v_fmamk_f32 v51, v64, 0x3e38aa3b, v70
	v_add_f32_e32 v18, 0, v18
	v_exp_f32_e32 v51, v51
	v_add_f32_e32 v18, v19, v18
	v_fmamk_f32 v19, v20, 0x3e38aa3b, v39
	v_exp_f32_e32 v19, v19
	v_fmamk_f32 v20, v21, 0x3e38aa3b, v39
	v_exp_f32_e32 v20, v20
	v_fmamk_f32 v21, v22, 0x3e38aa3b, v39
	v_exp_f32_e32 v21, v21
	v_fmamk_f32 v22, v23, 0x3e38aa3b, v39
	v_exp_f32_e32 v22, v22
	v_add_f32_e32 v18, v19, v18
	v_fmamk_f32 v19, v24, 0x3e38aa3b, v39
	v_add_f32_e32 v18, v20, v18
	v_exp_f32_e32 v19, v19
	v_fmamk_f32 v20, v25, 0x3e38aa3b, v39
	v_add_f32_e32 v18, v21, v18
	v_exp_f32_e32 v20, v20
	v_fmamk_f32 v21, v26, 0x3e38aa3b, v39
	v_add_f32_e32 v18, v22, v18
	v_exp_f32_e32 v21, v21
	v_fmamk_f32 v22, v27, 0x3e38aa3b, v39
	v_exp_f32_e32 v22, v22
	v_add_f32_e32 v18, v19, v18
	v_fmamk_f32 v19, v28, 0x3e38aa3b, v39
	v_add_f32_e32 v18, v20, v18
	v_exp_f32_e32 v19, v19
	v_fmamk_f32 v20, v29, 0x3e38aa3b, v39
	v_add_f32_e32 v18, v21, v18
; #define KLOAD(t) do { const bf16* kp_ = Kb + (size_t)((t) * 64 + sr) * 1024 + sc; ks0 = *reinterpret_cast<const bf16x8*>(kp_); ks1 = *reinterpret_cast<const bf16x8*>(kp_ + 32 * 1024); } while (0)
; #define VLOAD(t) do { const bf16* vp_ = Vb + (size_t)((t) * 64 + sr) * 1024 + sc; vs0 = *reinterpret_cast<const bf16x8*>(vp_); vs1 = *reinterpret_cast<const bf16x8*>(vp_ + 32 * 1024); } while (0)
; template <bool DIFF> ...
;     ...
;       stat_upd(a1, m1, l1, C, cb1);
;       if (DIFF) stat_upd(b1, m2, l2, C, cb1);
;     }
;   }
;   { auto rr = __builtin_amdgcn_permlane32_swap(__float_as_uint(l1), __float_as_uint(l1), false, false); l1 = __uint_as_float(rr[0]) + __uint_as_float(rr[1]); }
;   }
;   if (DIFF) { auto rr = __builtin_amdgcn_permlane32_swap(__float_as_uint(l2), __float_as_uint(l2), false, false); l2 = __uint_as_float(rr[0]) + __uint_as_float(rr[1]); }
;   float* const wsc = (float*)(lds + 34816) + wid * 64;
;   const float e1 = DIFF ? -m1 * C - __builtin_amdgcn_logf(l1) : 0.f, e2 = DIFF ? -m2 * C + __builtin_amdgcn_logf(fabsf(lam) / l2) : 0.f, nsg = lam < 0.f ? 1.f : -1.f;
;   f32x16 o[4];
; #pragma unroll
;   for (int d = 0; d < 4; ++d) o[d] = f32x16{};
;   KLOAD(t_lo); VLOAD(t_lo);
	v_exp_f32_e32 v20, v20
	v_fmamk_f32 v21, v30, 0x3e38aa3b, v39
	v_add_f32_e32 v18, v22, v18
	v_exp_f32_e32 v21, v21
	v_fmamk_f32 v22, v31, 0x3e38aa3b, v39
	v_exp_f32_e32 v22, v22
	v_add_f32_e32 v18, v19, v18
	v_add_f32_e32 v18, v20, v18
	v_add_f32_e32 v18, v21, v18
	v_add_f32_e32 v18, v22, v18
	v_max_f32_e32 v22, v3, v3
	v_max_f32_e32 v23, v2, v2
	v_max_f32_e32 v22, v23, v22
	v_max3_f32 v22, v22, v4, v5
	v_max3_f32 v22, v22, v6, v7
	v_max3_f32 v22, v22, v8, v9
	v_max3_f32 v22, v22, v10, v11
	v_max3_f32 v22, v22, v12, v13
	v_max3_f32 v22, v22, v14, v15
	v_max3_f32 v22, v22, v16, v17
	v_mov_b32_e32 v23, v22
	s_nop 1
	v_permlane32_swap_b32_e32 v22, v23
	v_max_f32_e32 v23, v23, v23
	v_max_f32_e32 v22, v22, v22
	v_max_f32_e32 v22, v22, v23
	v_add_f32_e32 v22, v68, v22
	v_max_f32_e32 v22, v54, v22
	v_sub_f32_e32 v23, v68, v22
	v_mul_f32_e32 v23, 0x3e38aa3b, v23
	v_fmamk_f32 v2, v2, 0x3e38aa3b, v23
	v_exp_f32_e32 v2, v2
	v_fmamk_f32 v3, v3, 0x3e38aa3b, v23
	v_exp_f32_e32 v3, v3
	v_fmamk_f32 v4, v4, 0x3e38aa3b, v23
	v_exp_f32_e32 v4, v4
	v_fmamk_f32 v5, v5, 0x3e38aa3b, v23
	v_exp_f32_e32 v5, v5
	v_fmamk_f32 v6, v6, 0x3e38aa3b, v23
	v_add_f32_e32 v2, 0, v2
	v_exp_f32_e32 v6, v6
	v_add_f32_e32 v2, v3, v2
	v_fmamk_f32 v3, v7, 0x3e38aa3b, v23
	v_add_f32_e32 v2, v4, v2
	v_exp_f32_e32 v3, v3
	v_fmamk_f32 v4, v8, 0x3e38aa3b, v23
	v_add_f32_e32 v2, v5, v2
	v_exp_f32_e32 v4, v4
	v_fmamk_f32 v5, v9, 0x3e38aa3b, v23
	v_add_f32_e32 v2, v6, v2
	v_exp_f32_e32 v5, v5
	v_fmamk_f32 v6, v10, 0x3e38aa3b, v23
	v_exp_f32_e32 v6, v6
	v_add_f32_e32 v2, v3, v2
	v_fmamk_f32 v3, v11, 0x3e38aa3b, v23
	v_add_f32_e32 v2, v4, v2
	v_exp_f32_e32 v3, v3
	v_fmamk_f32 v4, v12, 0x3e38aa3b, v23
	v_add_f32_e32 v2, v5, v2
	v_exp_f32_e32 v4, v4
	v_fmamk_f32 v5, v13, 0x3e38aa3b, v23
	v_add_f32_e32 v2, v6, v2
	v_exp_f32_e32 v5, v5
	v_fmamk_f32 v6, v14, 0x3e38aa3b, v23
	v_exp_f32_e32 v6, v6
	v_add_f32_e32 v2, v3, v2
	v_add_f32_e32 v2, v4, v2
	v_fmamk_f32 v3, v15, 0x3e38aa3b, v23
	v_add_f32_e32 v2, v5, v2
	v_exp_f32_e32 v3, v3
	v_fmamk_f32 v4, v16, 0x3e38aa3b, v23
	v_fmac_f32_e32 v70, 0x3e38aa3b, v65
	v_sub_f32_e32 v53, v87, v69
	v_fmamk_f32 v19, v32, 0x3e38aa3b, v39
	v_add_f32_e32 v2, v6, v2
	v_exp_f32_e32 v4, v4
	v_fmac_f32_e32 v23, 0x3e38aa3b, v17
	v_sub_f32_e32 v6, v54, v22
	v_exp_f32_e32 v52, v70
	v_mul_f32_e32 v53, 0x3e38aa3b, v53
	v_exp_f32_e32 v19, v19
	v_fmac_f32_e32 v39, 0x3e38aa3b, v33
	v_sub_f32_e32 v21, v69, v38
	v_exp_f32_e32 v5, v23
	v_mul_f32_e32 v6, 0x3e38aa3b, v6
	v_exp_f32_e32 v53, v53
	v_exp_f32_e32 v20, v39
	v_mul_f32_e32 v21, 0x3e38aa3b, v21
	v_exp_f32_e32 v6, v6
	v_exp_f32_e32 v21, v21
	v_add_f32_e32 v2, v3, v2
	v_add_f32_e32 v50, v51, v50
	v_add_f32_e32 v2, v4, v2
	v_add_f32_e32 v50, v52, v50
	v_add_f32_e32 v18, v19, v18
	v_add_f32_e32 v2, v5, v2
	v_fmac_f32_e32 v50, v83, v53
	v_add_f32_e32 v18, v20, v18
	v_fmac_f32_e32 v2, v1, v6
	v_fmac_f32_e32 v18, v50, v21
	v_mov_b32_e32 v3, v2
	v_mov_b32_e32 v1, v18
	s_nop 0
	v_permlane32_swap_b32_e32 v2, v3
	v_permlane32_swap_b32_e32 v18, v1
	v_add_f32_e32 v2, v2, v3
	v_and_b32_e32 v3, 0x7fffffff, v159
	v_add_f32_e32 v1, v18, v1
	v_div_scale_f32 v4, s[34:35], v2, v2, v3
	v_log_f32_e32 v1, v1
	v_rcp_f32_e32 v5, v4
	s_addc_u32 s7, s45, s7
	s_lshl_b32 s38, s38, 1
	v_fma_f32 v188, v38, s69, -v1
	v_fma_f32 v1, -v4, v5, 1.0
	v_fmac_f32_e32 v5, v1, v5
	v_div_scale_f32 v1, vcc, v3, v2, v3
	v_mul_f32_e32 v3, v1, v5
	v_fma_f32 v7, -v4, v3, v1
	v_fmac_f32_e32 v3, v7, v5
	s_add_u32 s6, s2, s38
	v_fma_f32 v1, -v4, v3, v1
	s_addc_u32 s7, s7, 0
	v_div_fmas_f32 v1, v1, v5, v3
	v_div_fixup_f32 v1, v1, v2, |v159|
	v_lshl_add_u64 v[2:3], v[76:77], 1, s[6:7]
	v_lshlrev_b32_e32 v146, 1, v72
	v_lshl_add_u64 v[2:3], v[2:3], 0, v[146:147]
	v_add_co_u32_e32 v4, vcc, s66, v2
	v_lshlrev_b32_e32 v41, 1, v75
	s_nop 0
	v_addc_co_u32_e32 v5, vcc, 0, v3, vcc
	global_load_dwordx4 v[136:139], v[2:3], off
	global_load_dwordx4 v[140:143], v[4:5], off
	v_log_f32_e32 v187, v1
	v_and_b32_e32 v41, 32, v41
	s_cmp_lg_u32 s90, -1
	v_or3_b32 v37, v37, v41, v42
	s_cselect_b32 s2, s90, 0
	v_lshl_add_u32 v1, v35, 6, 0
	v_mov_b32_e32 v0, 0
	v_and_b32_e32 v6, 48, v74
	v_add_u32_e32 v146, s2, v37
	v_lshl_add_u32 v2, v34, 9, v1
	v_lshl_add_u32 v1, v36, 9, v1
	s_lshl_b32 s2, s48, 17
	v_fmac_f32_e32 v187, 0xbe38aa3b, v22
	s_add_u32 s2, s2, 0x20000
	v_sub_u32_e32 v191, v73, v164
	v_lshl_add_u64 v[150:151], s[8:9], 0, v[78:79]
	v_lshl_add_u64 v[152:153], s[10:11], 0, v[78:79]
	s_mov_b64 s[34:35], 0
	v_add_u32_e32 v189, v2, v6
	v_add_u32_e32 v190, v1, v6
	v_mov_b32_e32 v1, v0
	v_mov_b32_e32 v2, v0
	v_mov_b32_e32 v3, v0
	v_mov_b32_e32 v4, v0
	v_mov_b32_e32 v5, v0
	v_mov_b32_e32 v6, v0
	v_mov_b32_e32 v7, v0
	v_mov_b32_e32 v8, v0
	v_mov_b32_e32 v9, v0
	v_mov_b32_e32 v10, v0
	v_mov_b32_e32 v11, v0
	v_mov_b32_e32 v12, v0
	v_mov_b32_e32 v13, v0
	v_mov_b32_e32 v14, v0
	v_mov_b32_e32 v15, v0
	v_mov_b32_e32 v16, v0
	v_mov_b32_e32 v17, v0
	v_mov_b32_e32 v18, v0
	v_mov_b32_e32 v19, v0
	v_mov_b32_e32 v20, v0
	v_mov_b32_e32 v21, v0
	v_mov_b32_e32 v22, v0
	v_mov_b32_e32 v23, v0
	v_mov_b32_e32 v24, v0
	v_mov_b32_e32 v25, v0
	v_mov_b32_e32 v26, v0
	v_mov_b32_e32 v27, v0
	v_mov_b32_e32 v28, v0
	v_mov_b32_e32 v29, v0
	v_mov_b32_e32 v30, v0
	v_mov_b32_e32 v31, v0
	v_mov_b32_e32 v32, v0
	v_mov_b32_e32 v33, v0
	v_mov_b32_e32 v34, v0
	v_mov_b32_e32 v35, v0
	v_mov_b32_e32 v36, v0
	v_mov_b32_e32 v37, v0
	v_mov_b32_e32 v38, v0
	v_mov_b32_e32 v39, v0
	v_mov_b32_e32 v40, v0
	v_mov_b32_e32 v41, v0
	v_mov_b32_e32 v42, v0
	v_mov_b32_e32 v43, v0
	v_mov_b32_e32 v44, v0
	v_mov_b32_e32 v45, v0
	v_mov_b32_e32 v46, v0
	v_mov_b32_e32 v47, v0
	v_mov_b32_e32 v48, v0
	v_mov_b32_e32 v49, v0
	v_mov_b32_e32 v50, v0
	v_mov_b32_e32 v51, v0
	v_mov_b32_e32 v52, v0
	v_mov_b32_e32 v53, v0
	v_mov_b32_e32 v54, v0
	v_mov_b32_e32 v55, v0
	v_mov_b32_e32 v56, v0
	v_mov_b32_e32 v57, v0
	v_mov_b32_e32 v58, v0
	v_mov_b32_e32 v59, v0
	v_mov_b32_e32 v60, v0
	v_mov_b32_e32 v61, v0
	v_mov_b32_e32 v62, v0
	v_mov_b32_e32 v63, v0
	s_mov_b32 s93, s91
	s_mov_b32 s98, 0x3e38aa3b
	s_mov_b32 s99, 0x3e38aa3b
	s_branch .LBB0_310
; #define SBAR() __builtin_amdgcn_sched_barrier(0)
; template <int KS> __device__ __forceinline__ void pv_step(f32x16* o, int vb, bf16x8 pa) {
;   const s16x4 l0 = tr_read<v_rd_off(0, KS, 0)>(vb), h0 = tr_read<v_rd_off(0, KS, 1)>(vb), l1 = tr_read<v_rd_off(1, KS, 0)>(vb), h1 = tr_read<v_rd_off(1, KS, 1)>(vb);
;   const s16x4 l2 = tr_read<v_rd_off(2, KS, 0)>(vb), h2 = tr_read<v_rd_off(2, KS, 1)>(vb), l3 = tr_read<v_rd_off(3, KS, 0)>(vb), h3 = tr_read<v_rd_off(3, KS, 1)>(vb);
;   asm volatile("s_waitcnt lgkmcnt(0)" ::: "memory"); SBAR();
;     ...
;   o[0] = __builtin_amdgcn_mfma_f32_32x32x16_bf16(pa, PK(l0, h0), o[0], 0, 0, 0);
;   o[1] = __builtin_amdgcn_mfma_f32_32x32x16_bf16(pa, PK(l1, h1), o[1], 0, 0, 0);
;   o[2] = __builtin_amdgcn_mfma_f32_32x32x16_bf16(pa, PK(l2, h2), o[2], 0, 0, 0);
;   o[3] = __builtin_amdgcn_mfma_f32_32x32x16_bf16(pa, PK(l3, h3), o[3], 0, 0, 0);
;     ...
; }
; template <bool DIFF> ...
;     ...
;       BIAS_APPLY(t, 1, a1, b1, cb1);
;       { const float x1 = fmaf(cb1, C, e1), x2 = fmaf(cb1, C, e2);
; #pragma unroll
;       for (int r = 0; r < 16; ++r) a1[r] = __builtin_amdgcn_exp2f(fmaf(a1[r], C, x1));
;       if (DIFF) {
; #pragma unroll
;         for (int r = 0; r < 16; ++r) a1[r] = fmaf(nsg, __builtin_amdgcn_exp2f(fmaf(b1[r], C, x2)), a1[r]);
;       } }
;       PK4(a1, 0, pa2); PK4(a1, 8, pa3);
;       SBAR();
;       pv_step<2>(o, vb0, pa2); pv_step<3>(o, vb0, pa3);
.LBB0_309:
	s_waitcnt lgkmcnt(0)
	v_fmamk_f32 v97, v96, 0x3e38aa3b, v188
	v_fmamk_f32 v96, v96, 0x3e38aa3b, v187
	v_mov_b32_e32 v230, v97
	v_mov_b32_e32 v231, v97
	v_pk_fma_f32 v[80:81], v[80:81], s[98:99], v[230:231]
	v_pk_fma_f32 v[82:83], v[82:83], s[98:99], v[230:231]
	v_pk_fma_f32 v[84:85], v[84:85], s[98:99], v[230:231]
	v_pk_fma_f32 v[86:87], v[86:87], s[98:99], v[230:231]
	v_pk_fma_f32 v[88:89], v[88:89], s[98:99], v[230:231]
	v_pk_fma_f32 v[90:91], v[90:91], s[98:99], v[230:231]
	v_pk_fma_f32 v[92:93], v[92:93], s[98:99], v[230:231]
	v_fmamk_f32 v94, v94, 0x3e38aa3b, v97
	v_fmac_f32_e32 v97, 0x3e38aa3b, v95
	v_mov_b32_e32 v230, v96
	v_mov_b32_e32 v231, v96
	v_pk_fma_f32 v[64:65], v[64:65], s[98:99], v[230:231]
	v_pk_fma_f32 v[66:67], v[66:67], s[98:99], v[230:231]
	v_pk_fma_f32 v[68:69], v[68:69], s[98:99], v[230:231]
	v_pk_fma_f32 v[70:71], v[70:71], s[98:99], v[230:231]
	v_pk_fma_f32 v[72:73], v[72:73], s[98:99], v[230:231]
	v_pk_fma_f32 v[74:75], v[74:75], s[98:99], v[230:231]
	v_pk_fma_f32 v[76:77], v[76:77], s[98:99], v[230:231]
	v_fmamk_f32 v78, v78, 0x3e38aa3b, v96
	v_fmac_f32_e32 v96, 0x3e38aa3b, v79
	v_exp_f32_e32 v80, v80
	v_exp_f32_e32 v81, v81
	v_exp_f32_e32 v82, v82
	v_exp_f32_e32 v83, v83
	v_exp_f32_e32 v84, v84
	v_exp_f32_e32 v85, v85
	v_exp_f32_e32 v86, v86
	v_exp_f32_e32 v87, v87
	v_exp_f32_e32 v88, v88
	v_exp_f32_e32 v89, v89
	v_exp_f32_e32 v90, v90
	v_exp_f32_e32 v91, v91
	v_exp_f32_e32 v92, v92
	v_exp_f32_e32 v93, v93
	v_exp_f32_e32 v94, v94
	v_exp_f32_e32 v95, v97
	v_exp_f32_e32 v64, v64
	v_exp_f32_e32 v65, v65
	v_exp_f32_e32 v66, v66
	v_exp_f32_e32 v67, v67
	v_exp_f32_e32 v68, v68
	v_exp_f32_e32 v69, v69
	v_exp_f32_e32 v70, v70
	v_exp_f32_e32 v71, v71
	v_exp_f32_e32 v72, v72
	v_exp_f32_e32 v73, v73
	v_exp_f32_e32 v74, v74
	v_exp_f32_e32 v75, v75
	v_exp_f32_e32 v76, v76
	v_exp_f32_e32 v77, v77
	v_exp_f32_e32 v78, v78
	v_exp_f32_e32 v79, v96
	v_pk_fma_f32 v[64:65], v[144:145], v[64:65], v[80:81]
	v_pk_fma_f32 v[66:67], v[144:145], v[66:67], v[82:83]
	v_pk_fma_f32 v[68:69], v[144:145], v[68:69], v[84:85]
	v_pk_fma_f32 v[70:71], v[144:145], v[70:71], v[86:87]
	v_pk_fma_f32 v[72:73], v[144:145], v[72:73], v[88:89]
	v_pk_fma_f32 v[74:75], v[144:145], v[74:75], v[90:91]
	v_pk_fma_f32 v[76:77], v[144:145], v[76:77], v[92:93]
	v_pk_fma_f32 v[78:79], v[144:145], v[78:79], v[94:95]
	v_cvt_pk_bf16_f32 v64, v64, v65
	v_cvt_pk_bf16_f32 v65, v66, v67
	v_cvt_pk_bf16_f32 v66, v68, v69
	v_cvt_pk_bf16_f32 v67, v70, v71
	v_cvt_pk_bf16_f32 v68, v72, v73
	v_cvt_pk_bf16_f32 v69, v74, v75
	v_cvt_pk_bf16_f32 v70, v76, v77
	v_cvt_pk_bf16_f32 v71, v78, v79
	v_permlane32_swap_b32_e32 v64, v66
	v_permlane32_swap_b32_e32 v65, v67
	v_permlane32_swap_b32_e32 v68, v70
	v_permlane32_swap_b32_e32 v69, v71
	ds_read_b64_tr_b16 v[72:73], v146 offset:0x2000
	ds_read_b64_tr_b16 v[74:75], v146 offset:0x2800
	ds_read_b64_tr_b16 v[76:77], v146 offset:0x2200
	ds_read_b64_tr_b16 v[78:79], v146 offset:0x2a00
	ds_read_b64_tr_b16 v[80:81], v146 offset:0x2400
	ds_read_b64_tr_b16 v[82:83], v146 offset:0x2c00
	ds_read_b64_tr_b16 v[84:85], v146 offset:0x2600
	ds_read_b64_tr_b16 v[86:87], v146 offset:0x2e00
	s_waitcnt lgkmcnt(0)
	s_nop 0
	v_mfma_f32_32x32x16_bf16 v[0:15], v[64:67], v[72:75], v[0:15]
	ds_read_b64_tr_b16 v[72:73], v146 offset:0x3000
	ds_read_b64_tr_b16 v[74:75], v146 offset:0x3800
	v_mfma_f32_32x32x16_bf16 v[16:31], v[64:67], v[76:79], v[16:31]
	ds_read_b64_tr_b16 v[76:77], v146 offset:0x3200
	ds_read_b64_tr_b16 v[78:79], v146 offset:0x3a00
	v_mfma_f32_32x32x16_bf16 v[32:47], v[64:67], v[80:83], v[32:47]
	ds_read_b64_tr_b16 v[80:81], v146 offset:0x3400
	ds_read_b64_tr_b16 v[82:83], v146 offset:0x3c00
	ds_read_b64_tr_b16 v[88:89], v146 offset:0x3600
	ds_read_b64_tr_b16 v[90:91], v146 offset:0x3e00
	s_waitcnt lgkmcnt(0)
	v_mfma_f32_32x32x16_bf16 v[48:63], v[64:67], v[84:87], v[48:63]
	v_mfma_f32_32x32x16_bf16 v[0:15], v[68:71], v[72:75], v[0:15]
	s_add_u32 s34, s34, 0x20000
	s_addc_u32 s35, s35, 0
	v_add_u32_e32 v173, 64, v173
	s_add_i32 s93, s93, 64
	s_cmp_eq_u32 s2, s34
	v_mfma_f32_32x32x16_bf16 v[16:31], v[68:71], v[76:79], v[16:31]
	v_mfma_f32_32x32x16_bf16 v[32:47], v[68:71], v[80:83], v[32:47]
	v_mfma_f32_32x32x16_bf16 v[48:63], v[68:71], v[88:91], v[48:63]
	s_cbranch_scc1 .LBB0_326

; #define SBAR() __builtin_amdgcn_sched_barrier(0)
; template <int KS> __device__ __forceinline__ void pv_step(f32x16* o, int vb, bf16x8 pa) {
;   const s16x4 l0 = tr_read<v_rd_off(0, KS, 0)>(vb), h0 = tr_read<v_rd_off(0, KS, 1)>(vb), l1 = tr_read<v_rd_off(1, KS, 0)>(vb), h1 = tr_read<v_rd_off(1, KS, 1)>(vb);
;   const s16x4 l2 = tr_read<v_rd_off(2, KS, 0)>(vb), h2 = tr_read<v_rd_off(2, KS, 1)>(vb), l3 = tr_read<v_rd_off(3, KS, 0)>(vb), h3 = tr_read<v_rd_off(3, KS, 1)>(vb);
;   asm volatile("s_waitcnt lgkmcnt(0)" ::: "memory"); SBAR();
;     ...
;   o[0] = __builtin_amdgcn_mfma_f32_32x32x16_bf16(pa, PK(l0, h0), o[0], 0, 0, 0);
;   o[1] = __builtin_amdgcn_mfma_f32_32x32x16_bf16(pa, PK(l1, h1), o[1], 0, 0, 0);
;   o[2] = __builtin_amdgcn_mfma_f32_32x32x16_bf16(pa, PK(l2, h2), o[2], 0, 0, 0);
;   o[3] = __builtin_amdgcn_mfma_f32_32x32x16_bf16(pa, PK(l3, h3), o[3], 0, 0, 0);
;     ...
; }
; template <bool DIFF> ...
;     ...
;       BIAS_APPLY(t, 0, a0, b0, cb0);
;       { const float x1 = fmaf(cb0, C, e1), x2 = fmaf(cb0, C, e2);
; #pragma unroll
;       for (int r = 0; r < 16; ++r) a0[r] = __builtin_amdgcn_exp2f(fmaf(a0[r], C, x1));
;       if (DIFF) {
; #pragma unroll
;         for (int r = 0; r < 16; ++r) a0[r] = fmaf(nsg, __builtin_amdgcn_exp2f(fmaf(b0[r], C, x2)), a0[r]);
;       } }
;       PK4(a0, 0, pa0); PK4(a0, 8, pa1);
;       SBAR();
;       pv_step<0>(o, vb0, pa0); pv_step<1>(o, vb0, pa1);
.LBB0_318:
	s_waitcnt lgkmcnt(0)
	v_fmamk_f32 v193, v192, 0x3e38aa3b, v188
	v_fmamk_f32 v192, v192, 0x3e38aa3b, v187
	v_mov_b32_e32 v230, v193
	v_mov_b32_e32 v231, v193
	v_pk_fma_f32 v[112:113], v[112:113], s[98:99], v[230:231]
	v_pk_fma_f32 v[114:115], v[114:115], s[98:99], v[230:231]
	v_pk_fma_f32 v[116:117], v[116:117], s[98:99], v[230:231]
	v_mov_b32_e32 v232, v192
	v_mov_b32_e32 v233, v192
	v_pk_fma_f32 v[96:97], v[96:97], s[98:99], v[232:233]
	v_pk_fma_f32 v[98:99], v[98:99], s[98:99], v[232:233]
	v_pk_fma_f32 v[100:101], v[100:101], s[98:99], v[232:233]
	v_exp_f32_e32 v112, v112
	v_exp_f32_e32 v113, v113
	v_exp_f32_e32 v114, v114
	v_exp_f32_e32 v115, v115
	v_exp_f32_e32 v116, v116
	v_exp_f32_e32 v117, v117
	v_pk_fma_f32 v[118:119], v[118:119], s[98:99], v[230:231]
	v_pk_fma_f32 v[120:121], v[120:121], s[98:99], v[230:231]
	v_pk_fma_f32 v[122:123], v[122:123], s[98:99], v[230:231]
	v_pk_fma_f32 v[124:125], v[124:125], s[98:99], v[230:231]
	v_fmamk_f32 v126, v126, 0x3e38aa3b, v193
	v_fmac_f32_e32 v193, 0x3e38aa3b, v127
	v_exp_f32_e32 v96, v96
	v_exp_f32_e32 v97, v97
	v_exp_f32_e32 v98, v98
	v_exp_f32_e32 v99, v99
	v_exp_f32_e32 v100, v100
	v_exp_f32_e32 v101, v101
	v_pk_fma_f32 v[102:103], v[102:103], s[98:99], v[232:233]
	v_pk_fma_f32 v[104:105], v[104:105], s[98:99], v[232:233]
	v_pk_fma_f32 v[106:107], v[106:107], s[98:99], v[232:233]
	v_pk_fma_f32 v[108:109], v[108:109], s[98:99], v[232:233]
	v_fmamk_f32 v110, v110, 0x3e38aa3b, v192
	v_fmac_f32_e32 v192, 0x3e38aa3b, v111
	v_exp_f32_e32 v118, v118
	v_exp_f32_e32 v119, v119
	v_exp_f32_e32 v120, v120
	v_exp_f32_e32 v121, v121
	v_exp_f32_e32 v122, v122
	v_exp_f32_e32 v123, v123
	v_exp_f32_e32 v124, v124
	v_exp_f32_e32 v125, v125
	v_exp_f32_e32 v126, v126
	v_exp_f32_e32 v127, v193
	v_exp_f32_e32 v102, v102
	v_exp_f32_e32 v103, v103
	v_exp_f32_e32 v104, v104
	v_exp_f32_e32 v105, v105
	v_exp_f32_e32 v106, v106
	v_exp_f32_e32 v107, v107
	v_exp_f32_e32 v108, v108
	v_exp_f32_e32 v109, v109
	v_exp_f32_e32 v110, v110
	v_exp_f32_e32 v111, v192
	v_pk_fma_f32 v[96:97], v[144:145], v[96:97], v[112:113]
	v_pk_fma_f32 v[98:99], v[144:145], v[98:99], v[114:115]
	v_pk_fma_f32 v[100:101], v[144:145], v[100:101], v[116:117]
	v_pk_fma_f32 v[102:103], v[144:145], v[102:103], v[118:119]
	v_pk_fma_f32 v[104:105], v[144:145], v[104:105], v[120:121]
	v_pk_fma_f32 v[106:107], v[144:145], v[106:107], v[122:123]
	v_pk_fma_f32 v[108:109], v[144:145], v[108:109], v[124:125]
	v_pk_fma_f32 v[110:111], v[144:145], v[110:111], v[126:127]
	v_cvt_pk_bf16_f32 v96, v96, v97
	v_cvt_pk_bf16_f32 v97, v98, v99
	v_cvt_pk_bf16_f32 v98, v100, v101
	v_cvt_pk_bf16_f32 v99, v102, v103
	s_nop 0
	v_permlane32_swap_b32_e32 v96, v98
	v_cvt_pk_bf16_f32 v100, v104, v105
	v_cvt_pk_bf16_f32 v101, v106, v107
	v_cvt_pk_bf16_f32 v102, v108, v109
	v_cvt_pk_bf16_f32 v103, v110, v111
	v_permlane32_swap_b32_e32 v97, v99
	v_permlane32_swap_b32_e32 v100, v102
	v_permlane32_swap_b32_e32 v101, v103
	ds_read_b64_tr_b16 v[104:105], v146 offset:0
	ds_read_b64_tr_b16 v[106:107], v146 offset:0x800
	ds_read_b64_tr_b16 v[108:109], v146 offset:0x200
	ds_read_b64_tr_b16 v[110:111], v146 offset:0xa00
	ds_read_b64_tr_b16 v[112:113], v146 offset:0x400
	ds_read_b64_tr_b16 v[114:115], v146 offset:0xc00
	ds_read_b64_tr_b16 v[116:117], v146 offset:0x600
	ds_read_b64_tr_b16 v[118:119], v146 offset:0xe00
	s_waitcnt lgkmcnt(0)
	s_nop 0
	v_mfma_f32_32x32x16_bf16 v[0:15], v[96:99], v[104:107], v[0:15]
	ds_read_b64_tr_b16 v[104:105], v146 offset:0x1000
	ds_read_b64_tr_b16 v[106:107], v146 offset:0x1800
	v_mfma_f32_32x32x16_bf16 v[16:31], v[96:99], v[108:111], v[16:31]
	ds_read_b64_tr_b16 v[108:109], v146 offset:0x1200
	ds_read_b64_tr_b16 v[110:111], v146 offset:0x1a00
	v_mfma_f32_32x32x16_bf16 v[32:47], v[96:99], v[112:115], v[32:47]
	ds_read_b64_tr_b16 v[112:113], v146 offset:0x1400
	ds_read_b64_tr_b16 v[114:115], v146 offset:0x1c00
	ds_read_b64_tr_b16 v[120:121], v146 offset:0x1600
	ds_read_b64_tr_b16 v[122:123], v146 offset:0x1e00
	s_waitcnt lgkmcnt(0)
	v_mfma_f32_32x32x16_bf16 v[48:63], v[96:99], v[116:119], v[48:63]
	v_mfma_f32_32x32x16_bf16 v[0:15], v[100:103], v[104:107], v[0:15]
	v_mfma_f32_32x32x16_bf16 v[16:31], v[100:103], v[108:111], v[16:31]
	v_mfma_f32_32x32x16_bf16 v[32:47], v[100:103], v[112:115], v[32:47]
	v_mfma_f32_32x32x16_bf16 v[48:63], v[100:103], v[120:123], v[48:63]
	s_cmpk_ge_i32 s93, 0x9f
	s_cbranch_scc1 .Lb2b_hi
	s_cmpk_le_i32 s93, 0xff41
	s_cbranch_scc1 .Lb2b_lo
	v_add3_u32 v96, v191, v173, s63
	v_med3_i32 v97, v96, 0, v163
	v_lshl_add_u32 v104, v97, 2, 0
	v_max_i32_e32 v97, -1, v96
	v_add_u32_e32 v97, 1, v97
	v_min_u32_e32 v97, 0x100, v97
	v_lshl_add_u32 v105, v97, 2, 0
	v_max_i32_e32 v97, -2, v96
	v_add_u32_e32 v97, 2, v97
	v_min_u32_e32 v97, 0x100, v97
	v_lshl_add_u32 v106, v97, 2, 0
	v_max_i32_e32 v97, -3, v96
	v_add_u32_e32 v97, 3, v97
	v_min_u32_e32 v97, 0x100, v97
	v_lshl_add_u32 v107, v97, 2, 0
	v_max_i32_e32 v97, -8, v96
	v_add_u32_e32 v97, 8, v97
	v_min_u32_e32 v97, 0x100, v97
	v_lshl_add_u32 v108, v97, 2, 0
	v_max_i32_e32 v97, -9, v96
	v_add_u32_e32 v97, 9, v97
	v_min_u32_e32 v97, 0x100, v97
	v_lshl_add_u32 v109, v97, 2, 0
	v_max_i32_e32 v97, -10, v96
	v_add_u32_e32 v97, 10, v97
	v_min_u32_e32 v97, 0x100, v97
	v_lshl_add_u32 v110, v97, 2, 0
	v_max_i32_e32 v97, -11, v96
	v_add_u32_e32 v97, 11, v97
	v_min_u32_e32 v97, 0x100, v97
	v_lshl_add_u32 v111, v97, 2, 0
	v_max_i32_e32 v97, -16, v96
	v_max_i32_e32 v98, 0xffffffef, v96
	v_max_i32_e32 v99, 0xffffffee, v96
	v_max_i32_e32 v100, 0xffffffed, v96
	v_max_i32_e32 v101, 0xffffffe8, v96
	v_max_i32_e32 v102, 0xffffffe7, v96
	v_max_i32_e32 v103, 0xffffffe6, v96
	v_add_u32_e32 v97, 16, v97
	v_add_u32_e32 v98, 17, v98
	v_add_u32_e32 v99, 18, v99
	v_add_u32_e32 v100, 19, v100
	v_add_u32_e32 v101, 24, v101
	v_add_u32_e32 v102, 25, v102
	v_add_u32_e32 v103, 26, v103
	v_max_i32_e32 v96, 0xffffffe5, v96
	v_min_u32_e32 v97, 0x100, v97
	v_min_u32_e32 v98, 0x100, v98
	v_min_u32_e32 v99, 0x100, v99
	v_min_u32_e32 v100, 0x100, v100
	v_min_u32_e32 v101, 0x100, v101
	v_min_u32_e32 v102, 0x100, v102
	v_min_u32_e32 v103, 0x100, v103
	v_add_u32_e32 v96, 27, v96
	v_lshl_add_u32 v97, v97, 2, 0
	v_lshl_add_u32 v98, v98, 2, 0
	v_lshl_add_u32 v99, v99, 2, 0
	v_lshl_add_u32 v100, v100, 2, 0
	v_lshl_add_u32 v101, v101, 2, 0
	v_lshl_add_u32 v102, v102, 2, 0
	v_lshl_add_u32 v103, v103, 2, 0
	v_min_u32_e32 v96, 0x100, v96
	v_lshl_add_u32 v112, v96, 2, 0
	ds_read_b32 v96, v97 offset:32768
	ds_read_b32 v97, v98 offset:32768
	ds_read_b32 v98, v99 offset:32768
	ds_read_b32 v99, v100 offset:32768
	ds_read_b32 v100, v101 offset:32768
	ds_read_b32 v101, v102 offset:32768
	ds_read_b32 v102, v103 offset:32768
	ds_read_b32 v103, v112 offset:32768
	ds_read_b32 v104, v104 offset:32768
	ds_read_b32 v105, v105 offset:32768
	ds_read_b32 v106, v106 offset:32768
	ds_read_b32 v107, v107 offset:32768
	ds_read_b32 v108, v108 offset:32768
	ds_read_b32 v109, v109 offset:32768
	ds_read_b32 v110, v110 offset:32768
	ds_read_b32 v111, v111 offset:32768
	s_waitcnt lgkmcnt(8)
	v_pk_add_f32 v[94:95], v[94:95], v[102:103]
	v_pk_add_f32 v[92:93], v[92:93], v[100:101]
	v_pk_add_f32 v[90:91], v[90:91], v[98:99]
	v_pk_add_f32 v[88:89], v[88:89], v[96:97]
	s_waitcnt lgkmcnt(0)
	v_pk_add_f32 v[86:87], v[86:87], v[110:111]
	v_pk_add_f32 v[84:85], v[84:85], v[108:109]
	v_pk_add_f32 v[82:83], v[82:83], v[106:107]
	v_pk_add_f32 v[80:81], v[80:81], v[104:105]
	v_pk_add_f32 v[78:79], v[78:79], v[102:103]
	v_pk_add_f32 v[76:77], v[76:77], v[100:101]
	v_pk_add_f32 v[74:75], v[74:75], v[98:99]
	v_pk_add_f32 v[72:73], v[72:73], v[96:97]
	v_pk_add_f32 v[70:71], v[70:71], v[110:111]
	v_pk_add_f32 v[68:69], v[68:69], v[108:109]
	v_pk_add_f32 v[66:67], v[66:67], v[106:107]
	v_pk_add_f32 v[64:65], v[64:65], v[104:105]
	v_mov_b32_e32 v96, 0
	s_branch .LBB0_309

; __global__ void __launch_bounds__(NTHR, 2) mega_fwd(Args a_unused) {
	.amdhsa_kernel _Z8mega_fwd4Args
		.amdhsa_group_segment_fixed_size 0
		.amdhsa_private_segment_fixed_size 0
		.amdhsa_kernarg_size 512
		.amdhsa_user_sgpr_count 2
		.amdhsa_user_sgpr_dispatch_ptr 0
		.amdhsa_user_sgpr_queue_ptr 0
		.amdhsa_user_sgpr_kernarg_segment_ptr 1
		.amdhsa_user_sgpr_dispatch_id 0
		.amdhsa_user_sgpr_kernarg_preload_length 0
		.amdhsa_user_sgpr_kernarg_preload_offset 0
		.amdhsa_user_sgpr_private_segment_size 0
		.amdhsa_uses_dynamic_stack 0
		.amdhsa_enable_private_segment 0
		.amdhsa_system_sgpr_workgroup_id_x 1
		.amdhsa_system_sgpr_workgroup_id_y 0
		.amdhsa_system_sgpr_workgroup_id_z 0
		.amdhsa_system_sgpr_workgroup_info 0
		.amdhsa_system_vgpr_workitem_id 2
		.amdhsa_next_free_vgpr 256
		.amdhsa_next_free_sgpr 100
		.amdhsa_accum_offset 256
		.amdhsa_reserve_vcc 1
		.amdhsa_float_round_mode_32 0
		.amdhsa_float_round_mode_16_64 0
		.amdhsa_float_denorm_mode_32 3
		.amdhsa_float_denorm_mode_16_64 3
		.amdhsa_dx10_clamp 1
		.amdhsa_ieee_mode 1
		.amdhsa_fp16_overflow 0
		.amdhsa_tg_split 0
		.amdhsa_exception_fp_ieee_invalid_op 0
		.amdhsa_exception_fp_denorm_src 0
		.amdhsa_exception_fp_ieee_div_zero 0
		.amdhsa_exception_fp_ieee_overflow 0
		.amdhsa_exception_fp_ieee_underflow 0
		.amdhsa_exception_fp_ieee_inexact 0
		.amdhsa_exception_int_div_zero 0
	.end_amdhsa_kernel

; __global__ void __launch_bounds__(NTHR, 2) mega_fwd(Args a_unused) {
amdhsa.kernels:
  - .agpr_count:     0
    .args:
      - .offset:         0
        .size:           256
        .value_kind:     by_value
      - .offset:         256
        .size:           4
        .value_kind:     hidden_block_count_x
      - .offset:         260
        .size:           4
        .value_kind:     hidden_block_count_y
      - .offset:         264
        .size:           4
        .value_kind:     hidden_block_count_z
      - .offset:         268
        .size:           2
        .value_kind:     hidden_group_size_x
      - .offset:         270
        .size:           2
        .value_kind:     hidden_group_size_y
      - .offset:         272
        .size:           2
        .value_kind:     hidden_group_size_z
      - .offset:         274
        .size:           2
        .value_kind:     hidden_remainder_x
      - .offset:         276
        .size:           2
        .value_kind:     hidden_remainder_y
      - .offset:         278
        .size:           2
        .value_kind:     hidden_remainder_z
      - .offset:         296
        .size:           8
        .value_kind:     hidden_global_offset_x
      - .offset:         304
        .size:           8
        .value_kind:     hidden_global_offset_y
      - .offset:         312
        .size:           8
        .value_kind:     hidden_global_offset_z
      - .offset:         320
        .size:           2
        .value_kind:     hidden_grid_dims
      - .offset:         344
        .size:           8
        .value_kind:     hidden_multigrid_sync_arg
      - .offset:         376
        .size:           4
        .value_kind:     hidden_dynamic_lds_size
    .group_segment_fixed_size: 0
    .kernarg_segment_align: 8
    .kernarg_segment_size: 512
    .language:       OpenCL C
    .language_version:
      - 2
      - 0
    .max_flat_workgroup_size: 512
    .name:           _Z8mega_fwd4Args
    .private_segment_fixed_size: 0
    .sgpr_count:     106
    .sgpr_spill_count: 59
    .symbol:         _Z8mega_fwd4Args.kd
    .uniform_work_group_size: 1
    .uses_dynamic_stack: false
    .vgpr_count:     256
    .vgpr_spill_count: 0
    .wavefront_size: 64
